# loop-edge edit: first super-step of each proj-GEMM K loop peeled with srcC=0, the 128 v_mov zero-init per tile deleted
# baseline (speedup 1.0000x reference)
; DEVI void phase_gemm_big(const Params& p, int mode, bf16_t* smem) {
;     ...
;     f32x4 acc[8][4];
; #pragma unroll
;     for (int i = 0; i < 8; ++i)
; #pragma unroll
;       for (int j = 0; j < 4; ++j) acc[i][j] = (f32x4){0.f, 0.f, 0.f, 0.f};
.Lg1_np:
.Lg1_peel:
	s_cmp_eq_u32 s69, 0
	s_cbranch_scc1 .Lg1_pw0
	s_mov_b32 s69, 0
	s_waitcnt vmcnt(32)
	s_branch .Lg1_pwd

; DEVI void lds_barrier() { asm volatile("s_waitcnt lgkmcnt(0)\n\ts_barrier" ::: "memory"); }
; #define SSTORE2(P, buf_) do { \
;     *(uint4*)(wA + (buf_) * 256 * GS2) = P##a0; *(uint4*)(wA + (buf_) * 256 * GS2 + 64 * GS2) = P##a1; \
;     *(uint4*)(wA + (buf_) * 256 * GS2 + 128 * GS2) = P##a2; *(uint4*)(wA + (buf_) * 256 * GS2 + 192 * GS2) = P##a3; \
;     *(uint4*)(wB + (buf_) * 128 * GS2) = P##b0; *(uint4*)(wB + (buf_) * 128 * GS2 + 64 * GS2) = P##b1; } while (0)
; DEVI void gemm_kloop2(const bf16_t* __restrict__ A, size_t lda, const bf16_t* __restrict__ Bt, size_t ldb,
;                       const bf16_t* __restrict__ nA, size_t nlda, const bf16_t* __restrict__ nBt, size_t nldb,
;                       bool first, bf16_t* smem, f32x4 (&acc)[8][4]) {
;     ...
; #pragma unroll 1
;   for (int kt = 0; kt < nk - 2; kt += 2) {
;     COMPUTE2(0, GLOAD2(x, gA, gB, lda, ldb, kt + 1));
;     SSTORE2(x, 1);
;     lds_barrier();
;     COMPUTE2(1, GLOAD2(x, gA, gB, lda, ldb, kt + 2));
.Lg1_pwd:
	s_barrier
	v_add_u32_e32 v130, s50, v212
	v_add_u32_e32 v131, s50, v213
	s_xor_b32 s16, s50, 0x8000
	s_add_u32 m0, s16, s52
	ds_read_b128 v[236:239], v192
	ds_read_b128 v[240:243], v192 offset:2048
	ds_read_b128 v[244:247], v192 offset:4096
	ds_read_b128 v[146:149], v192 offset:6144
	ds_read_b128 v[150:153], v193
	ds_read_b128 v[154:157], v193 offset:2048
	ds_read_b128 v[158:161], v193 offset:4096
	ds_read_b128 v[162:165], v193 offset:6144
	ds_read_b128 v[168:171], v130
	ds_read_b128 v[172:175], v130 offset:2048
	ds_read_b128 v[176:179], v130 offset:4096
	ds_read_b128 v[180:183], v130 offset:6144
	ds_read_b128 v[184:187], v130 offset:8192
	ds_read_b128 v[188:191], v130 offset:10240
	ds_read_b128 v[228:231], v130 offset:12288
	global_load_lds_dwordx4 v200, s[86:87]
	global_load_lds_dwordx4 v201, s[86:87] offset:1024
	global_load_lds_dwordx4 v202, s[86:87] offset:2048
	global_load_lds_dwordx4 v203, s[86:87] offset:3072
	s_add_u32 m0, m0, 0x1000
	s_nop 0
	global_load_lds_dwordx4 v204, s[86:87]
	global_load_lds_dwordx4 v205, s[86:87] offset:1024
	global_load_lds_dwordx4 v206, s[86:87] offset:2048
	global_load_lds_dwordx4 v207, s[86:87] offset:3072
	s_waitcnt lgkmcnt(7)
	s_barrier
	s_mov_b32 m0, s53
	s_nop 0
	global_load_lds_dwordx4 v208, s[56:57]
	global_load_lds_dwordx4 v209, s[56:57] offset:1024
	global_load_lds_dwordx4 v210, s[56:57] offset:2048
	global_load_lds_dwordx4 v211, s[56:57] offset:3072
	ds_read_b128 v[232:235], v130 offset:14336
	s_waitcnt lgkmcnt(7)
	v_mfma_f32_16x16x32_bf16 v[114:117], v[236:239], v[168:171], 0
	v_mfma_f32_16x16x32_bf16 v[102:105], v[240:243], v[168:171], 0
	v_mfma_f32_16x16x32_bf16 v[94:97], v[244:247], v[168:171], 0
	v_mfma_f32_16x16x32_bf16 v[86:89], v[146:149], v[168:171], 0
	s_waitcnt lgkmcnt(6)
	v_mfma_f32_16x16x32_bf16 v[126:129], v[236:239], v[172:175], 0
	v_mfma_f32_16x16x32_bf16 v[122:125], v[240:243], v[172:175], 0
	ds_read_b128 v[168:171], v131
	v_mfma_f32_16x16x32_bf16 v[118:121], v[244:247], v[172:175], 0
	v_mfma_f32_16x16x32_bf16 v[110:113], v[146:149], v[172:175], 0
	s_waitcnt lgkmcnt(6)
	v_mfma_f32_16x16x32_bf16 v[106:109], v[236:239], v[176:179], 0
	v_mfma_f32_16x16x32_bf16 v[98:101], v[240:243], v[176:179], 0
	ds_read_b128 v[172:175], v131 offset:2048
	v_mfma_f32_16x16x32_bf16 v[90:93], v[244:247], v[176:179], 0
	v_mfma_f32_16x16x32_bf16 v[82:85], v[146:149], v[176:179], 0
	s_waitcnt lgkmcnt(6)
	v_mfma_f32_16x16x32_bf16 v[78:81], v[236:239], v[180:183], 0
	v_mfma_f32_16x16x32_bf16 v[74:77], v[240:243], v[180:183], 0
	ds_read_b128 v[176:179], v131 offset:4096
	v_mfma_f32_16x16x32_bf16 v[70:73], v[244:247], v[180:183], 0
	v_mfma_f32_16x16x32_bf16 v[66:69], v[146:149], v[180:183], 0
	s_waitcnt lgkmcnt(6)
	v_mfma_f32_16x16x32_bf16 v[62:65], v[236:239], v[184:187], 0
	v_mfma_f32_16x16x32_bf16 v[58:61], v[240:243], v[184:187], 0
	ds_read_b128 v[180:183], v131 offset:6144
	v_mfma_f32_16x16x32_bf16 v[54:57], v[244:247], v[184:187], 0
	v_mfma_f32_16x16x32_bf16 v[50:53], v[146:149], v[184:187], 0
	s_waitcnt lgkmcnt(6)
	v_mfma_f32_16x16x32_bf16 v[46:49], v[236:239], v[188:191], 0
	v_mfma_f32_16x16x32_bf16 v[42:45], v[240:243], v[188:191], 0
	ds_read_b128 v[184:187], v131 offset:8192
	v_mfma_f32_16x16x32_bf16 v[38:41], v[244:247], v[188:191], 0
	v_mfma_f32_16x16x32_bf16 v[34:37], v[146:149], v[188:191], 0
	s_waitcnt lgkmcnt(6)
	v_mfma_f32_16x16x32_bf16 v[30:33], v[236:239], v[228:231], 0
	v_mfma_f32_16x16x32_bf16 v[26:29], v[240:243], v[228:231], 0
	ds_read_b128 v[188:191], v131 offset:10240
	v_mfma_f32_16x16x32_bf16 v[22:25], v[244:247], v[228:231], 0
	v_mfma_f32_16x16x32_bf16 v[18:21], v[146:149], v[228:231], 0
	s_waitcnt lgkmcnt(6)
	v_mfma_f32_16x16x32_bf16 v[14:17], v[236:239], v[232:235], 0
	v_mfma_f32_16x16x32_bf16 v[10:13], v[240:243], v[232:235], 0
	ds_read_b128 v[228:231], v131 offset:12288
	v_mfma_f32_16x16x32_bf16 v[6:9], v[244:247], v[232:235], 0
	v_mfma_f32_16x16x32_bf16 v[2:5], v[146:149], v[232:235], 0
	s_waitcnt lgkmcnt(6)
	v_mfma_f32_16x16x32_bf16 v[114:117], v[150:153], v[168:171], v[114:117]
	v_mfma_f32_16x16x32_bf16 v[102:105], v[154:157], v[168:171], v[102:105]
	ds_read_b128 v[232:235], v131 offset:14336
	v_mfma_f32_16x16x32_bf16 v[94:97], v[158:161], v[168:171], v[94:97]
	v_mfma_f32_16x16x32_bf16 v[86:89], v[162:165], v[168:171], v[86:89]
	s_add_u32 s86, s86, 0x80
	s_waitcnt lgkmcnt(6)
	v_mfma_f32_16x16x32_bf16 v[126:129], v[150:153], v[172:175], v[126:129]
	v_mfma_f32_16x16x32_bf16 v[122:125], v[154:157], v[172:175], v[122:125]
	v_mfma_f32_16x16x32_bf16 v[118:121], v[158:161], v[172:175], v[118:121]
	v_mfma_f32_16x16x32_bf16 v[110:113], v[162:165], v[172:175], v[110:113]
	s_addc_u32 s87, s87, 0
	s_waitcnt lgkmcnt(5)
	v_mfma_f32_16x16x32_bf16 v[106:109], v[150:153], v[176:179], v[106:109]
	v_mfma_f32_16x16x32_bf16 v[98:101], v[154:157], v[176:179], v[98:101]
	v_mfma_f32_16x16x32_bf16 v[90:93], v[158:161], v[176:179], v[90:93]
	v_mfma_f32_16x16x32_bf16 v[82:85], v[162:165], v[176:179], v[82:85]
	s_add_u32 s56, s56, 0x80
	s_waitcnt lgkmcnt(4)
	v_mfma_f32_16x16x32_bf16 v[78:81], v[150:153], v[180:183], v[78:81]
	v_mfma_f32_16x16x32_bf16 v[74:77], v[154:157], v[180:183], v[74:77]
	v_mfma_f32_16x16x32_bf16 v[70:73], v[158:161], v[180:183], v[70:73]
	v_mfma_f32_16x16x32_bf16 v[66:69], v[162:165], v[180:183], v[66:69]
	s_addc_u32 s57, s57, 0
	s_waitcnt lgkmcnt(3)
	v_mfma_f32_16x16x32_bf16 v[62:65], v[150:153], v[184:187], v[62:65]
	v_mfma_f32_16x16x32_bf16 v[58:61], v[154:157], v[184:187], v[58:61]
	v_mfma_f32_16x16x32_bf16 v[54:57], v[158:161], v[184:187], v[54:57]
	v_mfma_f32_16x16x32_bf16 v[50:53], v[162:165], v[184:187], v[50:53]
	s_xor_b32 s50, s50, 0x8000
	s_waitcnt lgkmcnt(2)
	v_mfma_f32_16x16x32_bf16 v[46:49], v[150:153], v[188:191], v[46:49]
	v_mfma_f32_16x16x32_bf16 v[42:45], v[154:157], v[188:191], v[42:45]
	v_mfma_f32_16x16x32_bf16 v[38:41], v[158:161], v[188:191], v[38:41]
	v_mfma_f32_16x16x32_bf16 v[34:37], v[162:165], v[188:191], v[34:37]
	s_add_u32 s65, s65, 1
	s_waitcnt lgkmcnt(1)
	v_mfma_f32_16x16x32_bf16 v[30:33], v[150:153], v[228:231], v[30:33]
	v_mfma_f32_16x16x32_bf16 v[26:29], v[154:157], v[228:231], v[26:29]
	v_mfma_f32_16x16x32_bf16 v[22:25], v[158:161], v[228:231], v[22:25]
	v_mfma_f32_16x16x32_bf16 v[18:21], v[162:165], v[228:231], v[18:21]
	s_cmp_eq_u32 s65, 15
	s_waitcnt lgkmcnt(0)
	v_mfma_f32_16x16x32_bf16 v[14:17], v[150:153], v[232:235], v[14:17]
	v_mfma_f32_16x16x32_bf16 v[10:13], v[154:157], v[232:235], v[10:13]
	v_mfma_f32_16x16x32_bf16 v[6:9], v[158:161], v[232:235], v[6:9]
	v_mfma_f32_16x16x32_bf16 v[2:5], v[162:165], v[232:235], v[2:5]
	s_cselect_b64 s[86:87], s[58:59], s[86:87]
	s_cselect_b64 s[56:57], s[60:61], s[56:57]
